# G2 merge GEMM: per-segment gate tiles requested three slices ahead into their own registers (scalar base + immediate offsets, counted vmcnt around them) instead of loaded and waited for at the segment
# baseline (speedup 1.0000x reference)
.LBB0_407:
	s_or_b64 exec, exec, s[20:21]
	v_readlane_b32 s8, v254, 46
	v_mov_b32_e32 v24, v1
	v_mov_b32_e32 v25, v1
	v_lshl_add_u32 v233, v0, 6, s8
	v_lshrrev_b32_e32 v0, 4, v233
	s_movk_i32 s8, 0xc0
	v_mul_lo_u32 v238, v0, s8
	s_nop 1
	v_readfirstlane_b32 s36, v238
	v_readfirstlane_b32 s37, v231
	v_readlane_b32 s32, v254, 47
	s_nop 3
	s_lshl_b32 s37, s37, 2
	s_lshr_b32 s32, s32, 4
	s_add_i32 s36, s36, s37
	s_add_i32 s36, s36, s32
	s_lshl_b32 s36, s36, 9
	s_add_u32 s36, s46, s36
	s_addc_u32 s37, s47, 0
	v_lshlrev_b32_e32 v0, 3, v200
	v_mov_b32_e32 v22, v1
	v_mov_b32_e32 v23, v1
	v_mov_b32_e32 v30, 0
	v_mov_b32_e32 v42, 0
	v_mov_b64_e32 v[36:37], v[24:25]
	v_add_u32_e32 v237, 0x800, v236
	v_or_b32_e32 v239, 0xc0, v238
	v_add_u32_e32 v240, 0x180, v238
	v_add_u32_e32 v241, 0x240, v238
	s_mov_b32 s8, 3
	v_lshl_add_u64 v[132:133], s[46:47], 0, v[0:1]
	s_mov_b64 s[20:21], 0
	v_mov_b64_e32 v[34:35], v[22:23]
	s_branch .LBB0_409

.LBB0_409:
	s_add_i32 s17, s8, -3
	s_cmp_lt_u32 s17, 46
	s_cselect_b64 s[22:23], -1, 0
	s_and_b32 s32, s17, 15
	s_cmp_eq_u32 s32, 14
	s_cbranch_scc1 .Lg2_w2
	s_cmp_gt_u32 s17, 45
	s_cbranch_scc1 .Lg2_w0a
	s_waitcnt vmcnt(3)
.LBB0_413:
	s_waitcnt lgkmcnt(0)
	s_cmp_gt_u32 s17, 44
	s_cselect_b64 s[24:25], -1, 0
	s_and_b64 vcc, exec, s[24:25]
	s_barrier
	s_and_b32 s28, s17, 2
	s_mulk_i32 s28, 0x6000
	v_add_u32_e32 v110, s28, v237
	ds_read_b128 v[106:109], v110
	ds_read_b128 v[242:245], v110 offset:1024
	s_cbranch_vccnz .Lgm_G2x_nodma0
	s_and_b32 s89, s8, 3
	s_mulk_i32 s89, 0x6000
	s_add_i32 s89, s89, s88
	s_mov_b32 m0, s89
	v_mfma_f32_16x16x32_bf16 v[102:105], v[14:17], v[26:29], v[102:105]
	v_mfma_f32_16x16x32_bf16 v[86:89], v[10:13], v[26:29], v[86:89]
	global_load_lds_dwordx4 v126, s[90:91]
	s_add_i32 m0, s89, 0x2000
	v_mfma_f32_16x16x32_bf16 v[70:73], v[6:9], v[26:29], v[70:73]
	v_mfma_f32_16x16x32_bf16 v[54:57], v[2:5], v[26:29], v[54:57]
	global_load_lds_dwordx4 v128, s[90:91]
	s_add_i32 m0, s89, 0x4000
	v_mfma_f32_16x16x32_bf16 v[98:101], v[14:17], v[18:21], v[98:101]
	v_mfma_f32_16x16x32_bf16 v[82:85], v[10:13], v[18:21], v[82:85]
	global_load_lds_dwordx4 v130, s[92:93]
	v_mfma_f32_16x16x32_bf16 v[66:69], v[6:9], v[18:21], v[66:69]
	v_mfma_f32_16x16x32_bf16 v[50:53], v[2:5], v[18:21], v[50:53]
	s_add_u32 s90, s90, 64
	s_addc_u32 s91, s91, 0
	s_add_u32 s92, s92, 64
	s_addc_u32 s93, s93, 0
	s_and_b32 s32, s17, 15
	s_cmp_eq_u32 s32, 12
	s_cbranch_scc1 .Lg2_gates
.LBB0_415:
	s_waitcnt lgkmcnt(0)
	s_barrier
	s_add_i32 s19, s8, -2
	s_and_b32 s29, s19, 3
	s_mulk_i32 s29, 0x6000
	v_add_u32_e32 v127, s29, v235
	v_add_u32_e32 v131, s29, v236
	ds_read_b128 v[26:29], v131
	v_mfma_f32_16x16x32_bf16 v[90:93], v[14:17], v[106:109], v[90:93]
	ds_read_b128 v[18:21], v131 offset:1024
	v_mfma_f32_16x16x32_bf16 v[74:77], v[10:13], v[106:109], v[74:77]
	ds_read_b128 v[118:121], v127
	v_mfma_f32_16x16x32_bf16 v[58:61], v[6:9], v[106:109], v[58:61]
	ds_read_b128 v[114:117], v127 offset:1024
	v_mfma_f32_16x16x32_bf16 v[46:49], v[2:5], v[106:109], v[46:49]
	ds_read_b128 v[110:113], v127 offset:2048
	ds_read_b128 v[106:109], v127 offset:3072
	v_mfma_f32_16x16x32_bf16 v[94:97], v[14:17], v[242:245], v[94:97]
	v_mfma_f32_16x16x32_bf16 v[78:81], v[10:13], v[242:245], v[78:81]
	v_mfma_f32_16x16x32_bf16 v[62:65], v[6:9], v[242:245], v[62:65]
	v_mfma_f32_16x16x32_bf16 v[42:45], v[2:5], v[242:245], v[42:45]
	s_and_b32 s32, s17, 15
	s_cmp_eq_u32 s32, 12
	s_cbranch_scc1 .Lg2_w1
	s_and_b64 vcc, exec, s[24:25]
	s_cbranch_vccnz .Lg2_w0b
	s_waitcnt vmcnt(3)
.LBB0_419:
	s_waitcnt lgkmcnt(0)
	s_barrier
	v_add_u32_e32 v129, s29, v237
	ds_read_b128 v[242:245], v129
	ds_read_b128 v[122:125], v129 offset:1024
	s_cmp_gt_u32 s17, 43
	s_cbranch_scc1 .Lgm_G2x_nodma1
	s_add_i32 s89, s28, s88
	s_mov_b32 m0, s89
	v_mfma_f32_16x16x32_bf16 v[102:105], v[118:121], v[26:29], v[102:105]
	v_mfma_f32_16x16x32_bf16 v[86:89], v[114:117], v[26:29], v[86:89]
	global_load_lds_dwordx4 v126, s[90:91]
	s_add_i32 m0, s89, 0x2000
	v_mfma_f32_16x16x32_bf16 v[70:73], v[110:113], v[26:29], v[70:73]
	v_mfma_f32_16x16x32_bf16 v[54:57], v[106:109], v[26:29], v[54:57]
	global_load_lds_dwordx4 v128, s[90:91]
	s_add_i32 m0, s89, 0x4000
	v_mfma_f32_16x16x32_bf16 v[98:101], v[118:121], v[18:21], v[98:101]
	v_mfma_f32_16x16x32_bf16 v[82:85], v[114:117], v[18:21], v[82:85]
	global_load_lds_dwordx4 v130, s[92:93]
	v_mfma_f32_16x16x32_bf16 v[66:69], v[110:113], v[18:21], v[66:69]
	v_mfma_f32_16x16x32_bf16 v[50:53], v[106:109], v[18:21], v[50:53]
	s_add_u32 s90, s90, 64
	s_addc_u32 s91, s91, 0
	s_add_u32 s92, s92, 64
	s_addc_u32 s93, s93, 0
.LBB0_421:
	s_waitcnt lgkmcnt(0)
	s_barrier
	v_mfma_f32_16x16x32_bf16 v[90:93], v[118:121], v[242:245], v[90:93]
	v_mfma_f32_16x16x32_bf16 v[74:77], v[114:117], v[242:245], v[74:77]
	v_mfma_f32_16x16x32_bf16 v[58:61], v[110:113], v[242:245], v[58:61]
	v_mfma_f32_16x16x32_bf16 v[46:49], v[106:109], v[242:245], v[46:49]
	s_andn2_b64 vcc, exec, s[22:23]
	s_cbranch_vccnz .LBB0_423
	s_add_i32 s22, s8, -1
	s_and_b32 s22, s22, 2
	s_mulk_i32 s22, 0x6000
	v_add_u32_e32 v18, s22, v235
	ds_read_b128 v[14:17], v18
	ds_read_b128 v[10:13], v18 offset:1024
	ds_read_b128 v[6:9], v18 offset:2048
	ds_read_b128 v[2:5], v18 offset:3072
	v_add_u32_e32 v129, s22, v236
	ds_read_b128 v[26:29], v129
	ds_read_b128 v[18:21], v129 offset:1024
.LBB0_423:
	v_mfma_f32_16x16x32_bf16 v[94:97], v[118:121], v[122:125], v[94:97]
	v_mfma_f32_16x16x32_bf16 v[78:81], v[114:117], v[122:125], v[78:81]
	v_mfma_f32_16x16x32_bf16 v[62:65], v[110:113], v[122:125], v[62:65]
	v_mfma_f32_16x16x32_bf16 v[42:45], v[106:109], v[122:125], v[42:45]
	s_and_b32 s19, s19, 15
	s_cmp_lg_u32 s19, 15
	s_cbranch_scc1 .LBB0_408
	s_nop 7
	s_nop 7
	v_lshlrev_b32_e32 v106, 16, v22
	v_and_b32_e32 v107, 0xffff0000, v22
	v_pk_fma_f32 v[196:197], v[102:103], v[106:107], v[196:197]
	v_lshlrev_b32_e32 v108, 16, v23
	v_and_b32_e32 v109, 0xffff0000, v23
	v_pk_fma_f32 v[194:195], v[104:105], v[108:109], v[194:195]
	v_lshlrev_b32_e32 v106, 16, v24
	v_and_b32_e32 v107, 0xffff0000, v24
	v_pk_fma_f32 v[192:193], v[98:99], v[106:107], v[192:193]
	v_lshlrev_b32_e32 v108, 16, v25
	v_and_b32_e32 v109, 0xffff0000, v25
	v_pk_fma_f32 v[190:191], v[100:101], v[108:109], v[190:191]
	v_lshlrev_b32_e32 v106, 16, v30
	v_and_b32_e32 v107, 0xffff0000, v30
	v_pk_fma_f32 v[188:189], v[90:91], v[106:107], v[188:189]
	v_lshlrev_b32_e32 v108, 16, v31
	v_and_b32_e32 v109, 0xffff0000, v31
	v_pk_fma_f32 v[186:187], v[92:93], v[108:109], v[186:187]
	v_lshlrev_b32_e32 v106, 16, v32
	v_and_b32_e32 v107, 0xffff0000, v32
	v_pk_fma_f32 v[184:185], v[94:95], v[106:107], v[184:185]
	v_lshlrev_b32_e32 v108, 16, v33
	v_and_b32_e32 v109, 0xffff0000, v33
	v_pk_fma_f32 v[182:183], v[96:97], v[108:109], v[182:183]
	v_lshlrev_b32_e32 v106, 16, v34
	v_and_b32_e32 v107, 0xffff0000, v34
	v_pk_fma_f32 v[180:181], v[86:87], v[106:107], v[180:181]
	v_lshlrev_b32_e32 v108, 16, v35
	v_and_b32_e32 v109, 0xffff0000, v35
	v_pk_fma_f32 v[178:179], v[88:89], v[108:109], v[178:179]
	v_lshlrev_b32_e32 v106, 16, v36
	v_and_b32_e32 v107, 0xffff0000, v36
	v_pk_fma_f32 v[176:177], v[82:83], v[106:107], v[176:177]
	v_lshlrev_b32_e32 v108, 16, v37
	v_and_b32_e32 v109, 0xffff0000, v37
	v_pk_fma_f32 v[174:175], v[84:85], v[108:109], v[174:175]
	v_lshlrev_b32_e32 v106, 16, v38
	v_and_b32_e32 v107, 0xffff0000, v38
	v_pk_fma_f32 v[172:173], v[74:75], v[106:107], v[172:173]
	v_lshlrev_b32_e32 v108, 16, v39
	v_and_b32_e32 v109, 0xffff0000, v39
	v_pk_fma_f32 v[170:171], v[76:77], v[108:109], v[170:171]
	v_lshlrev_b32_e32 v106, 16, v40
	v_and_b32_e32 v107, 0xffff0000, v40
	v_pk_fma_f32 v[168:169], v[78:79], v[106:107], v[168:169]
	v_lshlrev_b32_e32 v108, 16, v41
	v_and_b32_e32 v109, 0xffff0000, v41
	v_pk_fma_f32 v[166:167], v[80:81], v[108:109], v[166:167]
	v_lshlrev_b32_e32 v106, 16, v246
	v_and_b32_e32 v107, 0xffff0000, v246
	v_pk_fma_f32 v[164:165], v[70:71], v[106:107], v[164:165]
	v_lshlrev_b32_e32 v108, 16, v247
	v_and_b32_e32 v109, 0xffff0000, v247
	v_pk_fma_f32 v[162:163], v[72:73], v[108:109], v[162:163]
	v_lshlrev_b32_e32 v106, 16, v248
	v_and_b32_e32 v107, 0xffff0000, v248
	v_pk_fma_f32 v[160:161], v[66:67], v[106:107], v[160:161]
	v_lshlrev_b32_e32 v108, 16, v249
	v_and_b32_e32 v109, 0xffff0000, v249
	v_pk_fma_f32 v[158:159], v[68:69], v[108:109], v[158:159]
	v_lshlrev_b32_e32 v106, 16, v250
	v_and_b32_e32 v107, 0xffff0000, v250
	v_pk_fma_f32 v[156:157], v[58:59], v[106:107], v[156:157]
	v_lshlrev_b32_e32 v108, 16, v251
	v_and_b32_e32 v109, 0xffff0000, v251
	v_pk_fma_f32 v[154:155], v[60:61], v[108:109], v[154:155]
	v_lshlrev_b32_e32 v106, 16, v238
	v_and_b32_e32 v107, 0xffff0000, v238
	v_pk_fma_f32 v[152:153], v[62:63], v[106:107], v[152:153]
	v_lshlrev_b32_e32 v108, 16, v239
	v_and_b32_e32 v109, 0xffff0000, v239
	v_pk_fma_f32 v[150:151], v[64:65], v[108:109], v[150:151]
	v_lshlrev_b32_e32 v106, 16, v240
	v_and_b32_e32 v107, 0xffff0000, v240
	v_pk_fma_f32 v[148:149], v[54:55], v[106:107], v[148:149]
	v_lshlrev_b32_e32 v108, 16, v241
	v_and_b32_e32 v109, 0xffff0000, v241
	v_pk_fma_f32 v[146:147], v[56:57], v[108:109], v[146:147]
	v_lshlrev_b32_e32 v106, 16, v132
	v_and_b32_e32 v107, 0xffff0000, v132
	v_pk_fma_f32 v[144:145], v[50:51], v[106:107], v[144:145]
	v_lshlrev_b32_e32 v108, 16, v133
	v_and_b32_e32 v109, 0xffff0000, v133
	v_pk_fma_f32 v[142:143], v[52:53], v[108:109], v[142:143]
	v_lshlrev_b32_e32 v106, 16, v198
	v_and_b32_e32 v107, 0xffff0000, v198
	v_pk_fma_f32 v[140:141], v[46:47], v[106:107], v[140:141]
	v_lshlrev_b32_e32 v108, 16, v199
	v_and_b32_e32 v109, 0xffff0000, v199
	v_pk_fma_f32 v[138:139], v[48:49], v[108:109], v[138:139]
	v_lshlrev_b32_e32 v106, 16, v226
	v_and_b32_e32 v107, 0xffff0000, v226
	v_pk_fma_f32 v[136:137], v[42:43], v[106:107], v[136:137]
	v_lshlrev_b32_e32 v108, 16, v227
	v_and_b32_e32 v109, 0xffff0000, v227
	v_pk_fma_f32 v[134:135], v[44:45], v[108:109], v[134:135]
	v_mov_b32_e32 v42, 0
	v_mov_b32_e32 v43, v42
	v_mov_b32_e32 v44, v42
	v_mov_b32_e32 v45, v42
	v_mov_b32_e32 v46, v42
	v_mov_b32_e32 v47, v42
	v_mov_b32_e32 v48, v42
	v_mov_b32_e32 v49, v42
	v_mov_b32_e32 v50, v42
	v_mov_b32_e32 v51, v42
	v_mov_b32_e32 v52, v42
	v_mov_b32_e32 v53, v42
	v_mov_b32_e32 v54, v42
	v_mov_b32_e32 v55, v42
	v_mov_b32_e32 v56, v42
	v_mov_b32_e32 v57, v42
	v_mov_b32_e32 v62, v42
	v_mov_b32_e32 v63, v42
	v_mov_b32_e32 v64, v42
	v_mov_b32_e32 v65, v42
	v_mov_b32_e32 v58, v42
	v_mov_b32_e32 v59, v42
	v_mov_b32_e32 v60, v42
	v_mov_b32_e32 v61, v42
	v_mov_b32_e32 v66, v42
	v_mov_b32_e32 v67, v42
	v_mov_b32_e32 v68, v42
	v_mov_b32_e32 v69, v42
	v_mov_b32_e32 v70, v42
	v_mov_b32_e32 v71, v42
	v_mov_b32_e32 v72, v42
	v_mov_b32_e32 v73, v42
	v_mov_b32_e32 v78, v42
	v_mov_b32_e32 v79, v42
	v_mov_b32_e32 v80, v42
	v_mov_b32_e32 v81, v42
	v_mov_b32_e32 v74, v42
	v_mov_b32_e32 v75, v42
	v_mov_b32_e32 v76, v42
	v_mov_b32_e32 v77, v42
	v_mov_b32_e32 v82, v42
	v_mov_b32_e32 v83, v42
	v_mov_b32_e32 v84, v42
	v_mov_b32_e32 v85, v42
	v_mov_b32_e32 v86, v42
	v_mov_b32_e32 v87, v42
	v_mov_b32_e32 v88, v42
	v_mov_b32_e32 v89, v42
	v_mov_b32_e32 v94, v42
	v_mov_b32_e32 v95, v42
	v_mov_b32_e32 v96, v42
	v_mov_b32_e32 v97, v42
	v_mov_b32_e32 v90, v42
	v_mov_b32_e32 v91, v42
	v_mov_b32_e32 v92, v42
	v_mov_b32_e32 v93, v42
	v_mov_b32_e32 v98, v42
	v_mov_b32_e32 v99, v42
	v_mov_b32_e32 v100, v42
	v_mov_b32_e32 v101, v42
	v_mov_b32_e32 v102, v42
	v_mov_b32_e32 v103, v42
	v_mov_b32_e32 v104, v42
	v_mov_b32_e32 v105, v42
	s_branch .LBB0_408

.Lg2_w0a:
	s_waitcnt vmcnt(0)
	s_branch .LBB0_413
.Lg2_w2:
	s_cmp_gt_u32 s17, 45
	s_cbranch_scc1 .Lg2_w2t
	s_waitcnt vmcnt(19)
	s_branch .LBB0_413
.Lg2_w2t:
	s_waitcnt vmcnt(16)
	s_branch .LBB0_413
.Lg2_w1:
	s_waitcnt vmcnt(19)
	s_branch .LBB0_419

.Lg2_gates:
	s_lshr_b32 s94, s17, 4
	s_lshl_b32 s94, s94, 15
	s_add_u32 s94, s36, s94
	s_addc_u32 s95, s37, 0
	global_load_dwordx2 v[22:23], v0, s[94:95] nt
	global_load_dwordx2 v[24:25], v0, s[94:95] offset:512 nt
	global_load_dwordx2 v[30:31], v0, s[94:95] offset:1024 nt
	global_load_dwordx2 v[32:33], v0, s[94:95] offset:1536 nt
	s_add_u32 s94, s94, 0x18000
	s_addc_u32 s95, s95, 0
	global_load_dwordx2 v[34:35], v0, s[94:95] nt
	global_load_dwordx2 v[36:37], v0, s[94:95] offset:512 nt
	global_load_dwordx2 v[38:39], v0, s[94:95] offset:1024 nt
	global_load_dwordx2 v[40:41], v0, s[94:95] offset:1536 nt
	s_add_u32 s94, s94, 0x18000
	s_addc_u32 s95, s95, 0
	global_load_dwordx2 v[246:247], v0, s[94:95] nt
	global_load_dwordx2 v[248:249], v0, s[94:95] offset:512 nt
	global_load_dwordx2 v[250:251], v0, s[94:95] offset:1024 nt
	global_load_dwordx2 v[238:239], v0, s[94:95] offset:1536 nt
	s_add_u32 s94, s94, 0x18000
	s_addc_u32 s95, s95, 0
	global_load_dwordx2 v[240:241], v0, s[94:95] nt
	global_load_dwordx2 v[132:133], v0, s[94:95] offset:512 nt
	global_load_dwordx2 v[198:199], v0, s[94:95] offset:1024 nt
	global_load_dwordx2 v[226:227], v0, s[94:95] offset:1536 nt
	s_branch .LBB0_415
